# mem_attn row max taken over raw scores and scaled once (exact: power-of-two scale), 64 fewer VALU per item-wave
# baseline (speedup 1.0000x reference)
; DI f32x4 mfma16(bf16x8 a, bf16x8 b, f32x4 c) { return __builtin_amdgcn_mfma_f32_16x16x32_bf16(a, b, c, 0, 0, 0); }
; DI void mem_attn_item(ldsp lds, const bf16_t* proj, int ldp, int qmcol, int gatecol, const bf16_t* kv, bf16_t* branch, int b0, int item, int tid, int wid, int lane, const bool stage = true) {
;     ...
;     f32x4 sacc[16];
; #pragma unroll
;     for (int t = 0; t < 16; ++t) {
;         sacc[t] = (f32x4){0.f, 0.f, 0.f, 0.f};
;         const ldsp ka = Kb + (16 * t + li) * KS + quad * 16;
; #pragma unroll
;         for (int ks = 0; ks < 2; ++ks) sacc[t] = mfma16(lds_rd8(ka + ks * 64), qf[ks], sacc[t]);
;     }
;     float mx = -INFINITY;
; #pragma unroll
;     for (int t = 0; t < 16; ++t)
; #pragma unroll
;         for (int j = 0; j < 4; ++j) { const float v = sacc[t][j] * 0.125f; sacc[t][j] = v; mx = fmaxf(mx, v); }
;     mx = fmaxf(mx, __shfl_xor(mx, 16)); mx = fmaxf(mx, __shfl_xor(mx, 32));
;     float den = 0.f;
; #pragma unroll
;     for (int t = 0; t < 16; ++t)
; #pragma unroll
;         for (int j = 0; j < 4; ++j) { const float pv = exp2f((sacc[t][j] - mx) * 1.4426950408889634f); sacc[t][j] = pv; den += pv; }
;     den += __shfl_xor(den, 16); den += __shfl_xor(den, 32);
.Lma_nobar_dil:
	ds_read_b128 v[4:7], v102
	ds_read_b128 v[8:11], v102 offset:64
	s_mov_b32 s14, 1
	s_waitcnt vmcnt(5) lgkmcnt(1)
	v_mfma_f32_16x16x32_bf16 v[4:7], v[4:7], v[70:73], 0
	ds_read_b128 v[108:111], v102 offset:32320
	s_waitcnt vmcnt(4) lgkmcnt(1)
	v_mfma_f32_16x16x32_bf16 v[66:69], v[8:11], v[0:3], v[4:7]
	ds_read_b128 v[8:11], v102 offset:2368
	s_nop 3
	ds_read_b128 v[4:7], v102 offset:2304
	s_waitcnt lgkmcnt(0)
	v_mfma_f32_16x16x32_bf16 v[4:7], v[4:7], v[70:73], 0
	v_mfma_f32_16x16x32_bf16 v[62:65], v[8:11], v[0:3], v[4:7]
	ds_read_b128 v[8:11], v102 offset:4672
	s_nop 5
	ds_read_b128 v[4:7], v102 offset:4608
	s_waitcnt lgkmcnt(0)
	v_mfma_f32_16x16x32_bf16 v[4:7], v[4:7], v[70:73], 0
	v_mfma_f32_16x16x32_bf16 v[58:61], v[8:11], v[0:3], v[4:7]
	ds_read_b128 v[8:11], v103 offset:64
	s_nop 5
	ds_read_b128 v[4:7], v103
	s_waitcnt lgkmcnt(0)
	v_mfma_f32_16x16x32_bf16 v[4:7], v[4:7], v[70:73], 0
	v_mfma_f32_16x16x32_bf16 v[54:57], v[8:11], v[0:3], v[4:7]
	ds_read_b128 v[8:11], v102 offset:9280
	s_nop 5
	ds_read_b128 v[4:7], v102 offset:9216
	s_waitcnt lgkmcnt(0)
	v_mfma_f32_16x16x32_bf16 v[4:7], v[4:7], v[70:73], 0
	v_mfma_f32_16x16x32_bf16 v[50:53], v[8:11], v[0:3], v[4:7]
	ds_read_b128 v[8:11], v102 offset:11584
	s_nop 5
	ds_read_b128 v[4:7], v102 offset:11520
	s_waitcnt lgkmcnt(0)
	v_mfma_f32_16x16x32_bf16 v[4:7], v[4:7], v[70:73], 0
	v_mfma_f32_16x16x32_bf16 v[46:49], v[8:11], v[0:3], v[4:7]
	ds_read_b128 v[8:11], v102 offset:13888
	s_nop 5
	ds_read_b128 v[4:7], v102 offset:13824
	s_waitcnt lgkmcnt(0)
	v_mfma_f32_16x16x32_bf16 v[4:7], v[4:7], v[70:73], 0
	v_mfma_f32_16x16x32_bf16 v[42:45], v[8:11], v[0:3], v[4:7]
	ds_read_b128 v[8:11], v104 offset:64
	s_nop 5
	ds_read_b128 v[4:7], v104
	s_waitcnt lgkmcnt(0)
	v_mfma_f32_16x16x32_bf16 v[4:7], v[4:7], v[70:73], 0
	v_mfma_f32_16x16x32_bf16 v[38:41], v[8:11], v[0:3], v[4:7]
	ds_read_b128 v[8:11], v102 offset:18496
	s_nop 5
	ds_read_b128 v[4:7], v102 offset:18432
	s_waitcnt lgkmcnt(0)
	v_mfma_f32_16x16x32_bf16 v[4:7], v[4:7], v[70:73], 0
	v_mfma_f32_16x16x32_bf16 v[34:37], v[8:11], v[0:3], v[4:7]
	ds_read_b128 v[8:11], v102 offset:20800
	s_nop 5
	ds_read_b128 v[4:7], v102 offset:20736
	s_waitcnt lgkmcnt(0)
	v_mfma_f32_16x16x32_bf16 v[4:7], v[4:7], v[70:73], 0
	v_mfma_f32_16x16x32_bf16 v[26:29], v[8:11], v[0:3], v[4:7]
	ds_read_b128 v[8:11], v102 offset:23104
	s_nop 5
	ds_read_b128 v[4:7], v102 offset:23040
	s_waitcnt lgkmcnt(0)
	v_mfma_f32_16x16x32_bf16 v[4:7], v[4:7], v[70:73], 0
	v_mfma_f32_16x16x32_bf16 v[22:25], v[8:11], v[0:3], v[4:7]
	ds_read_b128 v[8:11], v105 offset:64
	s_nop 5
	ds_read_b128 v[4:7], v105
	s_waitcnt lgkmcnt(0)
	v_mfma_f32_16x16x32_bf16 v[4:7], v[4:7], v[70:73], 0
	v_mfma_f32_16x16x32_bf16 v[14:17], v[8:11], v[0:3], v[4:7]
	ds_read_b128 v[8:11], v102 offset:27712
	s_nop 5
	ds_read_b128 v[4:7], v102 offset:27648
	s_waitcnt lgkmcnt(0)
	v_mfma_f32_16x16x32_bf16 v[4:7], v[4:7], v[70:73], 0
	v_mfma_f32_16x16x32_bf16 v[18:21], v[8:11], v[0:3], v[4:7]
	ds_read_b128 v[8:11], v102 offset:30016
	s_nop 5
	ds_read_b128 v[4:7], v102 offset:29952
	s_waitcnt lgkmcnt(0)
	v_mfma_f32_16x16x32_bf16 v[4:7], v[4:7], v[70:73], 0
	v_mfma_f32_16x16x32_bf16 v[8:11], v[8:11], v[0:3], v[4:7]
	s_nop 6
	ds_read_b128 v[4:7], v102 offset:32256
	s_waitcnt lgkmcnt(0)
	v_mfma_f32_16x16x32_bf16 v[4:7], v[4:7], v[70:73], 0
	v_mfma_f32_16x16x32_bf16 v[4:7], v[108:111], v[0:3], v[4:7]
	ds_read_b128 v[108:111], v106
	s_waitcnt lgkmcnt(0)
	v_mfma_f32_16x16x32_bf16 v[70:73], v[108:111], v[70:73], 0
	ds_read_b128 v[108:111], v106 offset:64
	s_waitcnt lgkmcnt(0)
	v_mfma_f32_16x16x32_bf16 v[0:3], v[108:111], v[0:3], v[70:73]
	s_nop 4
	v_max3_f32 v70, v66, s15, v67
	v_max3_f32 v70, v70, v68, v69
	v_max3_f32 v70, v70, v62, v63
	v_max3_f32 v70, v70, v64, v65
	v_max3_f32 v70, v70, v58, v59
	v_max3_f32 v70, v70, v60, v61
	v_max3_f32 v70, v70, v54, v55
	v_max3_f32 v70, v70, v56, v57
	v_max3_f32 v70, v70, v50, v51
	v_max3_f32 v70, v70, v52, v53
	v_max3_f32 v70, v70, v46, v47
	v_max3_f32 v70, v70, v48, v49
	v_max3_f32 v70, v70, v42, v43
	v_max3_f32 v70, v70, v44, v45
	v_max3_f32 v70, v70, v38, v39
	v_max3_f32 v70, v70, v40, v41
	v_max3_f32 v70, v70, v34, v35
	v_max3_f32 v70, v70, v36, v37
	v_max3_f32 v70, v70, v26, v27
	v_max3_f32 v70, v70, v28, v29
	v_max3_f32 v70, v70, v22, v23
	v_max3_f32 v70, v70, v24, v25
	v_max3_f32 v70, v70, v14, v15
	v_max3_f32 v70, v70, v16, v17
	v_max3_f32 v70, v70, v18, v19
	v_max3_f32 v70, v70, v20, v21
	v_max3_f32 v70, v70, v8, v9
	v_max3_f32 v70, v70, v10, v11
	v_max3_f32 v70, v70, v4, v5
	v_max3_f32 v70, v70, v6, v7
	v_max3_f32 v70, v70, v0, v1
	v_max3_f32 v70, v70, v2, v3
	v_mul_f32_e32 v70, 0x3e000000, v70
	ds_bpermute_b32 v71, v33, v70
	v_min3_f32 v224, v66, v67, v68
	v_min3_f32 v224, v224, v69, v62
	v_min3_f32 v224, v224, v63, v64
	v_min3_f32 v224, v224, v65, v58
	v_min3_f32 v224, v224, v59, v60
	v_min3_f32 v224, v224, v61, v54
	v_min3_f32 v224, v224, v55, v56
	v_min3_f32 v224, v224, v57, v50
	v_min3_f32 v224, v224, v51, v52
	v_min3_f32 v224, v224, v53, v46
	v_min3_f32 v224, v224, v47, v48
	v_min3_f32 v224, v224, v49, v42
	v_min3_f32 v224, v224, v43, v44
	v_min3_f32 v224, v224, v45, v38
	v_min3_f32 v224, v224, v39, v40
	v_min3_f32 v224, v224, v41, v34
	s_waitcnt lgkmcnt(0)
	v_max_f32_e32 v71, v71, v71
	v_max_f32_e32 v70, v70, v71
	ds_bpermute_b32 v71, v96, v70
	v_min3_f32 v224, v224, v35, v36
	v_min3_f32 v224, v224, v37, v26
	v_min3_f32 v224, v224, v27, v28
	v_min3_f32 v224, v224, v29, v22
	v_min3_f32 v224, v224, v23, v24
	v_min3_f32 v224, v224, v25, v14
	v_min3_f32 v224, v224, v15, v16
	v_min3_f32 v224, v224, v17, v18
	v_min3_f32 v224, v224, v19, v20
	v_min3_f32 v224, v224, v21, v8
	v_min3_f32 v224, v224, v9, v10
	v_min3_f32 v224, v224, v11, v4
	v_min3_f32 v224, v224, v5, v6
	v_min3_f32 v224, v224, v7, v0
	v_min3_f32 v224, v224, v1, v2
	v_min_f32_e32 v224, v224, v3
	s_waitcnt lgkmcnt(0)
	v_max_f32_e32 v71, v71, v71
	v_max_f32_e32 v85, v70, v71
	v_fma_f32 v225, v224, s85, -v85
	v_mul_f32_e32 v225, 0x3fb8aa3b, v225
	v_cmp_gt_f32_e32 vcc, s86, v225
	s_cbranch_vccnz .Lma_slow_dil
; DI unsigned cvt_pk_bf16(float lo, float hi) { const f32x2_t v = {lo, hi}; const bf16v2_t b = __builtin_convertvector(v, bf16v2_t); return __builtin_bit_cast(unsigned, b); }
; DI f32x4 mfma16(bf16x8 a, bf16x8 b, f32x4 c) { return __builtin_amdgcn_mfma_f32_16x16x32_bf16(a, b, c, 0, 0, 0); }
; DI void mem_attn_item(ldsp lds, const bf16_t* proj, int ldp, int qmcol, int gatecol, const bf16_t* kv, bf16_t* branch, int b0, int item, int tid, int wid, int lane, const bool stage = true) {
;     ...
;     float den = 0.f;
; #pragma unroll
;     for (int t = 0; t < 16; ++t)
; #pragma unroll
;         for (int j = 0; j < 4; ++j) { const float pv = exp2f((sacc[t][j] - mx) * 1.4426950408889634f); sacc[t][j] = pv; den += pv; }
;     den += __shfl_xor(den, 16); den += __shfl_xor(den, 32);
;     f32x4 oacc[4];
; #pragma unroll
;     for (int dt = 0; dt < 4; ++dt) oacc[dt] = (f32x4){0.f, 0.f, 0.f, 0.f};
; #pragma unroll
;     for (int kt = 0; kt < 8; ++kt) {
;         u32x4 pw; pw.x = cvt_pk_bf16(sacc[2 * kt][0], sacc[2 * kt][1]); pw.y = cvt_pk_bf16(sacc[2 * kt][2], sacc[2 * kt][3]);
;         pw.z = cvt_pk_bf16(sacc[2 * kt + 1][0], sacc[2 * kt + 1][1]); pw.w = cvt_pk_bf16(sacc[2 * kt + 1][2], sacc[2 * kt + 1][3]);
;         const bf16x8 pf = __builtin_bit_cast(bf16x8, pw);
;         const ldsp va = Vb + (32 * kt + quad * 4 + (li >> 2)) * KS + (li & 3) * 8;
; #pragma unroll
;         for (int dt = 0; dt < 4; ++dt) oacc[dt] = mfma16(lds_tr8(va + dt * 32, va + 16 * KS + dt * 32), pf, oacc[dt]);
	v_fma_f32 v66, v66, s85, -v85
	v_mul_f32_e32 v70, 0x3fb8aa3b, v66
	v_fma_f32 v67, v67, s85, -v85
	v_fma_f32 v68, v68, s85, -v85
	v_exp_f32_e32 v66, v70
	v_mul_f32_e32 v71, 0x3fb8aa3b, v68
	v_fma_f32 v69, v69, s85, -v85
	v_mul_f32_e32 v70, 0x3fb8aa3b, v67
	v_fma_f32 v62, v62, s85, -v85
	v_fma_f32 v63, v63, s85, -v85
	v_exp_f32_e32 v67, v70
	v_fma_f32 v58, v58, s85, -v85
	v_exp_f32_e32 v68, v71
	v_add_f32_e32 v70, v66, v67
	v_fma_f32 v59, v59, s85, -v85
	v_mul_f32_e32 v71, 0x3fb8aa3b, v69
	v_add_f32_e32 v70, v68, v70
	v_fma_f32 v60, v60, s85, -v85
	v_exp_f32_e32 v69, v71
	v_fma_f32 v61, v61, s85, -v85
	v_fma_f32 v54, v54, s85, -v85
	v_add_f32_e32 v71, v69, v70
	v_mul_f32_e32 v70, 0x3fb8aa3b, v62
	v_fma_f32 v55, v55, s85, -v85
	v_fma_f32 v56, v56, s85, -v85
	v_exp_f32_e32 v62, v70
	v_fma_f32 v57, v57, s85, -v85
	v_fma_f32 v50, v50, s85, -v85
	v_mov_b32_e32 v70, v62
	v_add_f32_e32 v62, v70, v71
	v_mul_f32_e32 v71, 0x3fb8aa3b, v63
	v_fma_f32 v51, v51, s85, -v85
	v_fma_f32 v52, v52, s85, -v85
	v_exp_f32_e32 v63, v71
	v_fma_f32 v53, v53, s85, -v85
	v_fma_f32 v46, v46, s85, -v85
	v_mov_b32_e32 v71, v63
	v_fma_f32 v63, v64, s85, -v85
	v_mul_f32_e32 v64, 0x3fb8aa3b, v63
	v_fma_f32 v47, v47, s85, -v85
	v_fma_f32 v48, v48, s85, -v85
	v_exp_f32_e32 v63, v64
	v_fma_f32 v49, v49, s85, -v85
	v_fma_f32 v42, v42, s85, -v85
	v_mov_b32_e32 v72, v63
	v_fma_f32 v63, v65, s85, -v85
	v_mul_f32_e32 v64, 0x3fb8aa3b, v63
	v_fma_f32 v43, v43, s85, -v85
	v_fma_f32 v44, v44, s85, -v85
	v_exp_f32_e32 v63, v64
	v_fma_f32 v45, v45, s85, -v85
	v_fma_f32 v38, v38, s85, -v85
	v_mov_b32_e32 v73, v63
	v_mul_f32_e32 v63, 0x3fb8aa3b, v58
	v_fma_f32 v39, v39, s85, -v85
	v_fma_f32 v40, v40, s85, -v85
	v_exp_f32_e32 v58, v63
	v_fma_f32 v41, v41, s85, -v85
	v_fma_f32 v34, v34, s85, -v85
	v_mul_f32_e32 v63, 0x3fb8aa3b, v59
	v_fma_f32 v35, v35, s85, -v85
	v_fma_f32 v36, v36, s85, -v85
	v_exp_f32_e32 v59, v63
	v_add_f32_e32 v62, v71, v62
	v_add_f32_e32 v62, v72, v62
	v_mul_f32_e32 v63, 0x3fb8aa3b, v60
	v_add_f32_e32 v62, v73, v62
	v_add_f32_e32 v62, v58, v62
	v_exp_f32_e32 v60, v63
	v_add_f32_e32 v62, v59, v62
	v_fma_f32 v37, v37, s85, -v85
	v_mul_f32_e32 v63, 0x3fb8aa3b, v61
	v_add_f32_e32 v62, v60, v62
	v_fma_f32 v26, v26, s85, -v85
	v_exp_f32_e32 v61, v63
	v_fma_f32 v27, v27, s85, -v85
	v_fma_f32 v28, v28, s85, -v85
	v_mul_f32_e32 v63, 0x3fb8aa3b, v54
	v_add_f32_e32 v62, v61, v62
	v_fma_f32 v29, v29, s85, -v85
	v_exp_f32_e32 v54, v63
	v_fma_f32 v22, v22, s85, -v85
	v_fma_f32 v23, v23, s85, -v85
	v_mul_f32_e32 v63, 0x3fb8aa3b, v55
	v_add_f32_e32 v62, v54, v62
	v_fma_f32 v24, v24, s85, -v85
	v_exp_f32_e32 v55, v63
	v_fma_f32 v25, v25, s85, -v85
	v_fma_f32 v14, v14, s85, -v85
	v_mul_f32_e32 v63, 0x3fb8aa3b, v56
	v_add_f32_e32 v62, v55, v62
	v_fma_f32 v15, v15, s85, -v85
	v_exp_f32_e32 v56, v63
	v_fma_f32 v8, v8, s85, -v85
	v_fma_f32 v9, v9, s85, -v85
	v_mul_f32_e32 v63, 0x3fb8aa3b, v57
	v_add_f32_e32 v62, v56, v62
	v_cvt_pk_bf16_f32 v66, v66, v67
	v_exp_f32_e32 v57, v63
	v_cvt_pk_bf16_f32 v67, v68, v69
	v_cvt_pk_bf16_f32 v68, v70, v71
	v_mul_f32_e32 v63, 0x3fb8aa3b, v50
	v_add_f32_e32 v62, v57, v62
	v_cvt_pk_bf16_f32 v69, v72, v73
	v_exp_f32_e32 v50, v63
	ds_read_b64_tr_b16 v[72:73], v97 offset:39168
	ds_read_b64_tr_b16 v[70:71], v97 offset:36864
	ds_read_b64_tr_b16 v[108:109], v97 offset:36896
	ds_read_b64_tr_b16 v[110:111], v97 offset:39200
	v_mul_f32_e32 v63, 0x3fb8aa3b, v51
	v_add_f32_e32 v62, v50, v62
	ds_read_b64_tr_b16 v[112:113], v97 offset:36928
	ds_read_b64_tr_b16 v[114:115], v97 offset:39232
	v_exp_f32_e32 v51, v63
	ds_read_b64_tr_b16 v[116:117], v97 offset:36960
	ds_read_b64_tr_b16 v[118:119], v97 offset:39264
	v_cvt_pk_bf16_f32 v58, v58, v59
	v_mul_f32_e32 v63, 0x3fb8aa3b, v52
	v_add_f32_e32 v62, v51, v62
	v_cvt_pk_bf16_f32 v59, v60, v61
	v_exp_f32_e32 v52, v63
	v_cvt_pk_bf16_f32 v60, v54, v55
	v_cvt_pk_bf16_f32 v61, v56, v57
	v_mul_f32_e32 v63, 0x3fb8aa3b, v53
	v_add_f32_e32 v62, v52, v62
	ds_read_b64_tr_b16 v[54:55], v97 offset:41472
	ds_read_b64_tr_b16 v[56:57], v97 offset:43776
	v_exp_f32_e32 v53, v63
	v_fma_f32 v10, v10, s85, -v85
	s_waitcnt lgkmcnt(8)
	v_mfma_f32_16x16x32_bf16 v[70:73], v[70:73], v[66:69], 0
	v_mul_f32_e32 v63, 0x3fb8aa3b, v46
	v_add_f32_e32 v62, v53, v62
	s_waitcnt lgkmcnt(0)
	v_mfma_f32_16x16x32_bf16 v[54:57], v[54:57], v[58:61], v[70:73]
	v_exp_f32_e32 v46, v63
	s_nop 2
	ds_read_b64_tr_b16 v[70:71], v97 offset:41504
	ds_read_b64_tr_b16 v[72:73], v97 offset:43808
	v_mfma_f32_16x16x32_bf16 v[108:111], v[108:111], v[66:69], 0
	v_mul_f32_e32 v63, 0x3fb8aa3b, v47
	v_add_f32_e32 v62, v46, v62
	v_fma_f32 v11, v11, s85, -v85
	v_exp_f32_e32 v47, v63
	s_waitcnt lgkmcnt(0)
	v_mfma_f32_16x16x32_bf16 v[70:73], v[70:73], v[58:61], v[108:111]
	s_nop 2
	ds_read_b64_tr_b16 v[108:109], v97 offset:41536
	ds_read_b64_tr_b16 v[110:111], v97 offset:43840
	v_mul_f32_e32 v63, 0x3fb8aa3b, v48
	v_add_f32_e32 v62, v47, v62
	v_mfma_f32_16x16x32_bf16 v[112:115], v[112:115], v[66:69], 0
	v_exp_f32_e32 v48, v63
	s_waitcnt lgkmcnt(0)
	v_mfma_f32_16x16x32_bf16 v[108:111], v[108:111], v[58:61], v[112:115]
	s_nop 2
	s_nop 1
	ds_read_b64_tr_b16 v[112:113], v97 offset:41568
	ds_read_b64_tr_b16 v[114:115], v97 offset:43872
	v_mul_f32_e32 v63, 0x3fb8aa3b, v49
	v_add_f32_e32 v62, v48, v62
	v_cvt_pk_bf16_f32 v50, v50, v51
	v_exp_f32_e32 v49, v63
	v_cvt_pk_bf16_f32 v51, v52, v53
	v_cvt_pk_bf16_f32 v52, v46, v47
	v_mul_f32_e32 v63, 0x3fb8aa3b, v42
	v_add_f32_e32 v62, v49, v62
	v_cvt_pk_bf16_f32 v53, v48, v49
	v_exp_f32_e32 v42, v63
	ds_read_b64_tr_b16 v[46:47], v97 offset:46080
	ds_read_b64_tr_b16 v[48:49], v97 offset:48384
	v_fma_f32 v4, v4, s85, -v85
	v_mul_f32_e32 v63, 0x3fb8aa3b, v43
	v_add_f32_e32 v62, v42, v62
	s_waitcnt lgkmcnt(0)
; DI unsigned cvt_pk_bf16(float lo, float hi) { const f32x2_t v = {lo, hi}; const bf16v2_t b = __builtin_convertvector(v, bf16v2_t); return __builtin_bit_cast(unsigned, b); }
; DI f32x4 mfma16(bf16x8 a, bf16x8 b, f32x4 c) { return __builtin_amdgcn_mfma_f32_16x16x32_bf16(a, b, c, 0, 0, 0); }
; DI void mem_attn_item(ldsp lds, const bf16_t* proj, int ldp, int qmcol, int gatecol, const bf16_t* kv, bf16_t* branch, int b0, int item, int tid, int wid, int lane, const bool stage = true) {
;     ...
; #pragma unroll
;     for (int kt = 0; kt < 8; ++kt) {
;         u32x4 pw; pw.x = cvt_pk_bf16(sacc[2 * kt][0], sacc[2 * kt][1]); pw.y = cvt_pk_bf16(sacc[2 * kt][2], sacc[2 * kt][3]);
;         pw.z = cvt_pk_bf16(sacc[2 * kt + 1][0], sacc[2 * kt + 1][1]); pw.w = cvt_pk_bf16(sacc[2 * kt + 1][2], sacc[2 * kt + 1][3]);
;         const bf16x8 pf = __builtin_bit_cast(bf16x8, pw);
;         const ldsp va = Vb + (32 * kt + quad * 4 + (li >> 2)) * KS + (li & 3) * 8;
; #pragma unroll
;         for (int dt = 0; dt < 4; ++dt) oacc[dt] = mfma16(lds_tr8(va + dt * 32, va + 16 * KS + dt * 32), pf, oacc[dt]);
;     }
	v_mfma_f32_16x16x32_bf16 v[46:49], v[46:49], v[50:53], v[54:57]
	v_exp_f32_e32 v43, v63
	s_nop 1
	ds_read_b64_tr_b16 v[54:55], v97 offset:46112
	ds_read_b64_tr_b16 v[56:57], v97 offset:48416
	v_mfma_f32_16x16x32_bf16 v[66:69], v[116:119], v[66:69], 0
	v_mul_f32_e32 v63, 0x3fb8aa3b, v44
	v_add_f32_e32 v62, v43, v62
	v_fma_f32 v5, v5, s85, -v85
	v_exp_f32_e32 v44, v63
	v_mfma_f32_16x16x32_bf16 v[58:61], v[112:115], v[58:61], v[66:69]
	s_nop 2
	ds_read_b64_tr_b16 v[66:67], v97 offset:46144
	ds_read_b64_tr_b16 v[68:69], v97 offset:48448
	v_mul_f32_e32 v63, 0x3fb8aa3b, v45
	v_add_f32_e32 v62, v44, v62
	s_waitcnt lgkmcnt(2)
	v_mfma_f32_16x16x32_bf16 v[54:57], v[54:57], v[50:53], v[70:73]
	v_exp_f32_e32 v45, v63
	s_nop 1
	ds_read_b64_tr_b16 v[70:71], v97 offset:46176
	ds_read_b64_tr_b16 v[72:73], v97 offset:48480
	v_cvt_pk_bf16_f32 v42, v42, v43
	v_mul_f32_e32 v63, 0x3fb8aa3b, v38
	v_add_f32_e32 v62, v45, v62
	v_cvt_pk_bf16_f32 v43, v44, v45
	v_exp_f32_e32 v38, v63
	v_fma_f32 v6, v6, s85, -v85
	s_waitcnt lgkmcnt(2)
	v_mfma_f32_16x16x32_bf16 v[66:69], v[66:69], v[50:53], v[108:111]
	v_mul_f32_e32 v63, 0x3fb8aa3b, v39
	v_add_f32_e32 v62, v38, v62
	s_waitcnt lgkmcnt(0)
	v_mfma_f32_16x16x32_bf16 v[50:53], v[70:73], v[50:53], v[58:61]
	v_exp_f32_e32 v39, v63
	v_fma_f32 v7, v7, s85, -v85
	v_fma_f32 v0, v0, s85, -v85
	v_mul_f32_e32 v63, 0x3fb8aa3b, v40
	v_add_f32_e32 v62, v39, v62
	v_cvt_pk_bf16_f32 v44, v38, v39
	v_exp_f32_e32 v40, v63
	v_fma_f32 v1, v1, s85, -v85
	v_fma_f32 v2, v2, s85, -v85
	v_mul_f32_e32 v63, 0x3fb8aa3b, v41
	v_add_f32_e32 v62, v40, v62
	v_fma_f32 v3, v3, s85, -v85
	v_exp_f32_e32 v41, v63
	v_mul_f32_e32 v63, 0x3fb8aa3b, v34
	v_add_f32_e32 v62, v41, v62
	v_cvt_pk_bf16_f32 v45, v40, v41
	v_exp_f32_e32 v34, v63
	ds_read_b64_tr_b16 v[38:39], v97 offset:50688
	ds_read_b64_tr_b16 v[40:41], v97 offset:52992
	s_waitcnt lgkmcnt(0)
	v_mfma_f32_16x16x32_bf16 v[38:41], v[38:41], v[42:45], v[46:49]
	v_mul_f32_e32 v63, 0x3fb8aa3b, v35
	v_add_f32_e32 v62, v34, v62
	s_nop 0
	ds_read_b64_tr_b16 v[46:47], v97 offset:50720
	ds_read_b64_tr_b16 v[48:49], v97 offset:53024
	v_exp_f32_e32 v35, v63
	s_waitcnt lgkmcnt(0)
	v_mfma_f32_16x16x32_bf16 v[46:49], v[46:49], v[42:45], v[54:57]
	s_nop 2
	ds_read_b64_tr_b16 v[54:55], v97 offset:50752
	ds_read_b64_tr_b16 v[56:57], v97 offset:53056
	v_mul_f32_e32 v63, 0x3fb8aa3b, v36
	v_add_f32_e32 v62, v35, v62
	ds_read_b64_tr_b16 v[58:59], v97 offset:50784
	ds_read_b64_tr_b16 v[60:61], v97 offset:53088
	v_exp_f32_e32 v36, v63
	s_waitcnt lgkmcnt(2)
	v_mfma_f32_16x16x32_bf16 v[54:57], v[54:57], v[42:45], v[66:69]
	v_cvt_pk_bf16_f32 v34, v34, v35
	v_mul_f32_e32 v63, 0x3fb8aa3b, v37
	v_add_f32_e32 v62, v36, v62
	s_waitcnt lgkmcnt(0)
	v_mfma_f32_16x16x32_bf16 v[42:45], v[58:61], v[42:45], v[50:53]
	v_exp_f32_e32 v37, v63
	s_nop 1
	ds_read_b64_tr_b16 v[50:51], v97 offset:55296
	ds_read_b64_tr_b16 v[52:53], v97 offset:57600
	v_mul_f32_e32 v63, 0x3fb8aa3b, v26
	v_add_f32_e32 v62, v37, v62
	v_cvt_pk_bf16_f32 v35, v36, v37
	v_exp_f32_e32 v26, v63
	v_mul_f32_e32 v63, 0x3fb8aa3b, v27
	v_add_f32_e32 v62, v26, v62
	s_nop 0
	v_exp_f32_e32 v27, v63
	s_nop 0
	v_add_f32_e32 v63, v27, v62
	v_mul_f32_e32 v62, 0x3fb8aa3b, v28
	v_cvt_pk_bf16_f32 v36, v26, v27
	s_nop 0
	v_exp_f32_e32 v28, v62
	s_nop 0
	v_mov_b32_e32 v62, v28
	v_add_f32_e32 v28, v62, v63
	v_mul_f32_e32 v63, 0x3fb8aa3b, v29
	s_nop 1
	v_exp_f32_e32 v29, v63
	s_nop 0
	v_mov_b32_e32 v63, v29
	v_mul_f32_e32 v29, 0x3fb8aa3b, v22
	v_add_f32_e32 v28, v63, v28
	v_cvt_pk_bf16_f32 v37, v62, v63
	v_exp_f32_e32 v22, v29
	s_waitcnt lgkmcnt(0)
	v_mfma_f32_16x16x32_bf16 v[38:41], v[50:53], v[34:37], v[38:41]
	ds_read_b64_tr_b16 v[50:51], v97 offset:55328
	ds_read_b64_tr_b16 v[52:53], v97 offset:57632
	v_mul_f32_e32 v29, 0x3fb8aa3b, v23
	v_add_f32_e32 v28, v22, v28
	s_waitcnt lgkmcnt(0)
	v_mfma_f32_16x16x32_bf16 v[46:49], v[50:53], v[34:37], v[46:49]
	v_exp_f32_e32 v23, v29
	ds_read_b64_tr_b16 v[50:51], v97 offset:55360
	ds_read_b64_tr_b16 v[52:53], v97 offset:57664
	s_waitcnt lgkmcnt(0)
	v_mfma_f32_16x16x32_bf16 v[50:53], v[50:53], v[34:37], v[54:57]
	v_mul_f32_e32 v29, 0x3fb8aa3b, v24
	v_add_f32_e32 v28, v23, v28
	s_nop 0
	ds_read_b64_tr_b16 v[54:55], v97 offset:55392
	ds_read_b64_tr_b16 v[56:57], v97 offset:57696
	v_exp_f32_e32 v24, v29
	s_waitcnt lgkmcnt(0)
; DI unsigned cvt_pk_bf16(float lo, float hi) { const f32x2_t v = {lo, hi}; const bf16v2_t b = __builtin_convertvector(v, bf16v2_t); return __builtin_bit_cast(unsigned, b); }
; DI f32x4 mfma16(bf16x8 a, bf16x8 b, f32x4 c) { return __builtin_amdgcn_mfma_f32_16x16x32_bf16(a, b, c, 0, 0, 0); }
; DI void mem_attn_item(ldsp lds, const bf16_t* proj, int ldp, int qmcol, int gatecol, const bf16_t* kv, bf16_t* branch, int b0, int item, int tid, int wid, int lane, const bool stage = true) {
;     ...
;     for (int t = 0; t < 16; ++t)
; #pragma unroll
;         for (int j = 0; j < 4; ++j) { const float pv = exp2f((sacc[t][j] - mx) * 1.4426950408889634f); sacc[t][j] = pv; den += pv; }
;     den += __shfl_xor(den, 16); den += __shfl_xor(den, 32);
;     f32x4 oacc[4];
; #pragma unroll
;     for (int dt = 0; dt < 4; ++dt) oacc[dt] = (f32x4){0.f, 0.f, 0.f, 0.f};
; #pragma unroll
;     for (int kt = 0; kt < 8; ++kt) {
;         u32x4 pw; pw.x = cvt_pk_bf16(sacc[2 * kt][0], sacc[2 * kt][1]); pw.y = cvt_pk_bf16(sacc[2 * kt][2], sacc[2 * kt][3]);
;         pw.z = cvt_pk_bf16(sacc[2 * kt + 1][0], sacc[2 * kt + 1][1]); pw.w = cvt_pk_bf16(sacc[2 * kt + 1][2], sacc[2 * kt + 1][3]);
;         const bf16x8 pf = __builtin_bit_cast(bf16x8, pw);
;         const ldsp va = Vb + (32 * kt + quad * 4 + (li >> 2)) * KS + (li & 3) * 8;
; #pragma unroll
;         for (int dt = 0; dt < 4; ++dt) oacc[dt] = mfma16(lds_tr8(va + dt * 32, va + 16 * KS + dt * 32), pf, oacc[dt]);
;     }
	v_mfma_f32_16x16x32_bf16 v[34:37], v[54:57], v[34:37], v[42:45]
	v_mul_f32_e32 v29, 0x3fb8aa3b, v25
	v_add_f32_e32 v28, v24, v28
	s_nop 0
	v_exp_f32_e32 v25, v29
	s_nop 0
	v_add_f32_e32 v29, v25, v28
	v_mul_f32_e32 v28, 0x3fb8aa3b, v14
	s_nop 1
	v_exp_f32_e32 v14, v28
	s_nop 0
	v_mov_b32_e32 v28, v14
	v_add_f32_e32 v14, v28, v29
	v_mul_f32_e32 v29, 0x3fb8aa3b, v15
	s_nop 1
	v_exp_f32_e32 v15, v29
	s_nop 0
	v_mov_b32_e32 v29, v15
	v_fma_f32 v15, v16, s85, -v85
	v_mul_f32_e32 v16, 0x3fb8aa3b, v15
	v_add_f32_e32 v14, v29, v14
	s_nop 0
	v_exp_f32_e32 v15, v16
	s_nop 0
	v_mov_b32_e32 v64, v15
	v_fma_f32 v15, v17, s85, -v85
	v_mul_f32_e32 v16, 0x3fb8aa3b, v15
	v_add_f32_e32 v14, v64, v14
	s_nop 0
	v_exp_f32_e32 v15, v16
	s_nop 0
	v_mov_b32_e32 v65, v15
	v_add_f32_e32 v15, v65, v14
	v_fma_f32 v14, v18, s85, -v85
	v_mul_f32_e32 v16, 0x3fb8aa3b, v14
	s_nop 1
	v_exp_f32_e32 v14, v16
	s_nop 0
	v_add_f32_e32 v16, v14, v15
	v_fma_f32 v15, v19, s85, -v85
	v_mul_f32_e32 v17, 0x3fb8aa3b, v15
	s_nop 1
	v_exp_f32_e32 v15, v17
	s_nop 0
	v_add_f32_e32 v17, v15, v16
	v_fma_f32 v16, v20, s85, -v85
	v_mul_f32_e32 v18, 0x3fb8aa3b, v16
	v_cvt_pk_bf16_f32 v20, v22, v23
	v_cvt_pk_bf16_f32 v22, v28, v29
	v_exp_f32_e32 v16, v18
	v_cvt_pk_bf16_f32 v23, v64, v65
	v_cvt_pk_bf16_f32 v14, v14, v15
	v_add_f32_e32 v18, v16, v17
	v_fma_f32 v17, v21, s85, -v85
	v_mul_f32_e32 v19, 0x3fb8aa3b, v17
	v_cvt_pk_bf16_f32 v21, v24, v25
	ds_read_b64_tr_b16 v[24:25], v97 offset:59904
	ds_read_b64_tr_b16 v[26:27], v97 offset:62208
	v_exp_f32_e32 v17, v19
	s_waitcnt lgkmcnt(0)
	v_mfma_f32_16x16x32_bf16 v[24:27], v[24:27], v[20:23], v[38:41]
	s_nop 2
	ds_read_b64_tr_b16 v[38:39], v97 offset:59936
	ds_read_b64_tr_b16 v[40:41], v97 offset:62240
	v_mul_f32_e32 v19, 0x3fb8aa3b, v8
	v_add_f32_e32 v18, v17, v18
	s_waitcnt lgkmcnt(0)
	v_mfma_f32_16x16x32_bf16 v[38:41], v[38:41], v[20:23], v[46:49]
	v_exp_f32_e32 v8, v19
	ds_read_b64_tr_b16 v[42:43], v97 offset:59968
	ds_read_b64_tr_b16 v[44:45], v97 offset:62272
	ds_read_b64_tr_b16 v[46:47], v97 offset:60000
	ds_read_b64_tr_b16 v[48:49], v97 offset:62304
	v_mul_f32_e32 v19, 0x3fb8aa3b, v9
	v_add_f32_e32 v18, v8, v18
	v_cvt_pk_bf16_f32 v15, v16, v17
	v_exp_f32_e32 v9, v19
	s_waitcnt lgkmcnt(2)
	v_mfma_f32_16x16x32_bf16 v[42:45], v[42:45], v[20:23], v[50:53]
	v_mul_f32_e32 v19, 0x3fb8aa3b, v10
	v_add_f32_e32 v18, v9, v18
	v_cvt_pk_bf16_f32 v16, v8, v9
	v_exp_f32_e32 v10, v19
	s_waitcnt lgkmcnt(0)
	v_mfma_f32_16x16x32_bf16 v[20:23], v[46:49], v[20:23], v[34:37]
	v_mul_f32_e32 v19, 0x3fb8aa3b, v11
	v_add_f32_e32 v18, v10, v18
	s_nop 0
	v_exp_f32_e32 v11, v19
	v_mul_f32_e32 v19, 0x3fb8aa3b, v4
	v_add_f32_e32 v18, v11, v18
	v_cvt_pk_bf16_f32 v17, v10, v11
	v_exp_f32_e32 v4, v19
	ds_read_b64_tr_b16 v[8:9], v97 offset:64512
	ds_read_b64_tr_b16 v[10:11], v98 offset:29952
	ds_read_b64_tr_b16 v[28:29], v98 offset:29984
	s_waitcnt lgkmcnt(1)
	v_mfma_f32_16x16x32_bf16 v[8:11], v[8:11], v[14:17], v[24:27]
	v_mul_f32_e32 v19, 0x3fb8aa3b, v5
	s_nop 1
	ds_read_b64_tr_b16 v[26:27], v97 offset:64544
	v_add_f32_e32 v18, v4, v18
	v_exp_f32_e32 v5, v19
	s_waitcnt lgkmcnt(0)
	v_mfma_f32_16x16x32_bf16 v[24:27], v[26:29], v[14:17], v[38:41]
	v_mul_f32_e32 v19, 0x3fb8aa3b, v6
	v_add_f32_e32 v18, v5, v18
	ds_read_b64_tr_b16 v[34:35], v97 offset:64576
	ds_read_b64_tr_b16 v[36:37], v98 offset:30016
	v_exp_f32_e32 v6, v19
	ds_read_b64_tr_b16 v[38:39], v97 offset:64608
	ds_read_b64_tr_b16 v[40:41], v98 offset:30048
	s_waitcnt lgkmcnt(0)
	v_mfma_f32_16x16x32_bf16 v[20:23], v[38:41], v[14:17], v[20:23]
	v_mul_f32_e32 v19, 0x3fb8aa3b, v7
	v_add_f32_e32 v18, v6, v18
	v_cvt_pk_bf16_f32 v38, v4, v5
	v_exp_f32_e32 v7, v19
	v_mfma_f32_16x16x32_bf16 v[34:37], v[34:37], v[14:17], v[42:45]
	v_mul_f32_e32 v19, 0x3fb8aa3b, v0
	v_add_f32_e32 v18, v7, v18
	v_cvt_pk_bf16_f32 v39, v6, v7
	v_exp_f32_e32 v0, v19
	v_mul_f32_e32 v19, 0x3fb8aa3b, v1
	v_add_f32_e32 v18, v0, v18
	s_nop 0
	v_exp_f32_e32 v1, v19
	v_mul_f32_e32 v19, 0x3fb8aa3b, v2
	v_add_f32_e32 v18, v1, v18
	v_cvt_pk_bf16_f32 v40, v0, v1
	v_exp_f32_e32 v2, v19
	v_mul_f32_e32 v19, 0x3fb8aa3b, v3
	v_add_f32_e32 v18, v2, v18
	s_nop 0
	v_exp_f32_e32 v3, v19
	s_branch .Lma_join_dil

; DI f32x4 mfma16(bf16x8 a, bf16x8 b, f32x4 c) { return __builtin_amdgcn_mfma_f32_16x16x32_bf16(a, b, c, 0, 0, 0); }
; DI void mem_attn_item(ldsp lds, const bf16_t* proj, int ldp, int qmcol, int gatecol, const bf16_t* kv, bf16_t* branch, int b0, int item, int tid, int wid, int lane, const bool stage = true) {
;     ...
;     f32x4 sacc[16];
; #pragma unroll
;     for (int t = 0; t < 16; ++t) {
;         sacc[t] = (f32x4){0.f, 0.f, 0.f, 0.f};
;         const ldsp ka = Kb + (16 * t + li) * KS + quad * 16;
; #pragma unroll
;         for (int ks = 0; ks < 2; ++ks) sacc[t] = mfma16(lds_rd8(ka + ks * 64), qf[ks], sacc[t]);
;     }
;     float mx = -INFINITY;
; #pragma unroll
;     for (int t = 0; t < 16; ++t)
; #pragma unroll
;         for (int j = 0; j < 4; ++j) { const float v = sacc[t][j] * 0.125f; sacc[t][j] = v; mx = fmaxf(mx, v); }
;     mx = fmaxf(mx, __shfl_xor(mx, 16)); mx = fmaxf(mx, __shfl_xor(mx, 32));
;     float den = 0.f;
; #pragma unroll
;     for (int t = 0; t < 16; ++t)
; #pragma unroll
;         for (int j = 0; j < 4; ++j) { const float pv = exp2f((sacc[t][j] - mx) * 1.4426950408889634f); sacc[t][j] = pv; den += pv; }
;     den += __shfl_xor(den, 16); den += __shfl_xor(den, 32);
.Lma_nobar_gla:
	ds_read_b128 v[4:7], v103
	ds_read_b128 v[8:11], v103 offset:64
	s_cmpk_eq_i32 s14, 0x400
	s_waitcnt vmcnt(5) lgkmcnt(1)
	v_mfma_f32_16x16x32_bf16 v[4:7], v[4:7], v[70:73], 0
	ds_read_b128 v[108:111], v103 offset:32320
	s_waitcnt vmcnt(4) lgkmcnt(1)
	v_mfma_f32_16x16x32_bf16 v[66:69], v[8:11], v[0:3], v[4:7]
	ds_read_b128 v[8:11], v103 offset:2368
	s_nop 3
	ds_read_b128 v[4:7], v103 offset:2304
	s_waitcnt lgkmcnt(0)
	v_mfma_f32_16x16x32_bf16 v[4:7], v[4:7], v[70:73], 0
	v_mfma_f32_16x16x32_bf16 v[62:65], v[8:11], v[0:3], v[4:7]
	ds_read_b128 v[8:11], v103 offset:4672
	s_nop 5
	ds_read_b128 v[4:7], v103 offset:4608
	s_waitcnt lgkmcnt(0)
	v_mfma_f32_16x16x32_bf16 v[4:7], v[4:7], v[70:73], 0
	v_mfma_f32_16x16x32_bf16 v[58:61], v[8:11], v[0:3], v[4:7]
	ds_read_b128 v[8:11], v104 offset:64
	s_nop 5
	ds_read_b128 v[4:7], v104
	s_waitcnt lgkmcnt(0)
	v_mfma_f32_16x16x32_bf16 v[4:7], v[4:7], v[70:73], 0
	v_mfma_f32_16x16x32_bf16 v[54:57], v[8:11], v[0:3], v[4:7]
	ds_read_b128 v[8:11], v103 offset:9280
	s_nop 5
	ds_read_b128 v[4:7], v103 offset:9216
	s_waitcnt lgkmcnt(0)
	v_mfma_f32_16x16x32_bf16 v[4:7], v[4:7], v[70:73], 0
	v_mfma_f32_16x16x32_bf16 v[50:53], v[8:11], v[0:3], v[4:7]
	ds_read_b128 v[8:11], v103 offset:11584
	s_nop 5
	ds_read_b128 v[4:7], v103 offset:11520
	s_waitcnt lgkmcnt(0)
	v_mfma_f32_16x16x32_bf16 v[4:7], v[4:7], v[70:73], 0
	v_mfma_f32_16x16x32_bf16 v[46:49], v[8:11], v[0:3], v[4:7]
	ds_read_b128 v[8:11], v103 offset:13888
	s_nop 5
	ds_read_b128 v[4:7], v103 offset:13824
	s_waitcnt lgkmcnt(0)
	v_mfma_f32_16x16x32_bf16 v[4:7], v[4:7], v[70:73], 0
	v_mfma_f32_16x16x32_bf16 v[42:45], v[8:11], v[0:3], v[4:7]
	ds_read_b128 v[8:11], v105 offset:64
	s_nop 5
	ds_read_b128 v[4:7], v105
	s_waitcnt lgkmcnt(0)
	v_mfma_f32_16x16x32_bf16 v[4:7], v[4:7], v[70:73], 0
	v_mfma_f32_16x16x32_bf16 v[38:41], v[8:11], v[0:3], v[4:7]
	ds_read_b128 v[8:11], v103 offset:18496
	s_nop 5
	ds_read_b128 v[4:7], v103 offset:18432
	s_waitcnt lgkmcnt(0)
	v_mfma_f32_16x16x32_bf16 v[4:7], v[4:7], v[70:73], 0
	v_mfma_f32_16x16x32_bf16 v[34:37], v[8:11], v[0:3], v[4:7]
	ds_read_b128 v[8:11], v103 offset:20800
	s_nop 5
	ds_read_b128 v[4:7], v103 offset:20736
	s_waitcnt lgkmcnt(0)
	v_mfma_f32_16x16x32_bf16 v[4:7], v[4:7], v[70:73], 0
	v_mfma_f32_16x16x32_bf16 v[26:29], v[8:11], v[0:3], v[4:7]
	ds_read_b128 v[8:11], v103 offset:23104
	s_nop 5
	ds_read_b128 v[4:7], v103 offset:23040
	s_waitcnt lgkmcnt(0)
	v_mfma_f32_16x16x32_bf16 v[4:7], v[4:7], v[70:73], 0
	v_mfma_f32_16x16x32_bf16 v[22:25], v[8:11], v[0:3], v[4:7]
	ds_read_b128 v[8:11], v106 offset:64
	s_nop 5
	ds_read_b128 v[4:7], v106
	s_waitcnt lgkmcnt(0)
	v_mfma_f32_16x16x32_bf16 v[4:7], v[4:7], v[70:73], 0
	v_mfma_f32_16x16x32_bf16 v[18:21], v[8:11], v[0:3], v[4:7]
	ds_read_b128 v[8:11], v103 offset:27712
	s_nop 5
	ds_read_b128 v[4:7], v103 offset:27648
	s_waitcnt lgkmcnt(0)
	v_mfma_f32_16x16x32_bf16 v[4:7], v[4:7], v[70:73], 0
	v_mfma_f32_16x16x32_bf16 v[14:17], v[8:11], v[0:3], v[4:7]
	ds_read_b128 v[8:11], v103 offset:30016
	s_nop 5
	ds_read_b128 v[4:7], v103 offset:29952
	s_waitcnt lgkmcnt(0)
	v_mfma_f32_16x16x32_bf16 v[4:7], v[4:7], v[70:73], 0
	v_mfma_f32_16x16x32_bf16 v[8:11], v[8:11], v[0:3], v[4:7]
	s_nop 6
	ds_read_b128 v[4:7], v103 offset:32256
	s_waitcnt lgkmcnt(0)
	v_mfma_f32_16x16x32_bf16 v[4:7], v[4:7], v[70:73], 0
	v_mfma_f32_16x16x32_bf16 v[4:7], v[108:111], v[0:3], v[4:7]
	ds_read_b128 v[108:111], v107
	s_waitcnt lgkmcnt(0)
	v_mfma_f32_16x16x32_bf16 v[70:73], v[108:111], v[70:73], 0
	ds_read_b128 v[108:111], v107 offset:64
	s_waitcnt lgkmcnt(0)
	v_mfma_f32_16x16x32_bf16 v[0:3], v[108:111], v[0:3], v[70:73]
	s_nop 4
	v_max3_f32 v70, v66, s15, v67
	v_max3_f32 v70, v70, v68, v69
	v_max3_f32 v70, v70, v62, v63
	v_max3_f32 v70, v70, v64, v65
	v_max3_f32 v70, v70, v58, v59
	v_max3_f32 v70, v70, v60, v61
	v_max3_f32 v70, v70, v54, v55
	v_max3_f32 v70, v70, v56, v57
	v_max3_f32 v70, v70, v50, v51
	v_max3_f32 v70, v70, v52, v53
	v_max3_f32 v70, v70, v46, v47
	v_max3_f32 v70, v70, v48, v49
	v_max3_f32 v70, v70, v42, v43
	v_max3_f32 v70, v70, v44, v45
	v_max3_f32 v70, v70, v38, v39
	v_max3_f32 v70, v70, v40, v41
	v_max3_f32 v70, v70, v34, v35
	v_max3_f32 v70, v70, v36, v37
	v_max3_f32 v70, v70, v26, v27
	v_max3_f32 v70, v70, v28, v29
	v_max3_f32 v70, v70, v22, v23
	v_max3_f32 v70, v70, v24, v25
	v_max3_f32 v70, v70, v18, v19
	v_max3_f32 v70, v70, v20, v21
	v_max3_f32 v70, v70, v14, v15
	v_max3_f32 v70, v70, v16, v17
	v_max3_f32 v70, v70, v8, v9
	v_max3_f32 v70, v70, v10, v11
	v_max3_f32 v70, v70, v4, v5
	v_max3_f32 v70, v70, v6, v7
	v_max3_f32 v70, v70, v0, v1
	v_max3_f32 v70, v70, v2, v3
	v_mul_f32_e32 v70, 0x3e000000, v70
	ds_bpermute_b32 v71, v33, v70
	v_min3_f32 v224, v66, v67, v68
	v_min3_f32 v224, v224, v69, v62
	v_min3_f32 v224, v224, v63, v64
	v_min3_f32 v224, v224, v65, v58
	v_min3_f32 v224, v224, v59, v60
	v_min3_f32 v224, v224, v61, v54
	v_min3_f32 v224, v224, v55, v56
	v_min3_f32 v224, v224, v57, v50
	v_min3_f32 v224, v224, v51, v52
	v_min3_f32 v224, v224, v53, v46
	v_min3_f32 v224, v224, v47, v48
	v_min3_f32 v224, v224, v49, v42
	v_min3_f32 v224, v224, v43, v44
	v_min3_f32 v224, v224, v45, v38
	v_min3_f32 v224, v224, v39, v40
	v_min3_f32 v224, v224, v41, v34
	s_waitcnt lgkmcnt(0)
	v_max_f32_e32 v71, v71, v71
	v_max_f32_e32 v70, v70, v71
	ds_bpermute_b32 v71, v96, v70
	v_min3_f32 v224, v224, v35, v36
	v_min3_f32 v224, v224, v37, v26
	v_min3_f32 v224, v224, v27, v28
	v_min3_f32 v224, v224, v29, v22
	v_min3_f32 v224, v224, v23, v24
	v_min3_f32 v224, v224, v25, v18
	v_min3_f32 v224, v224, v19, v20
	v_min3_f32 v224, v224, v21, v14
	v_min3_f32 v224, v224, v15, v16
	v_min3_f32 v224, v224, v17, v8
	v_min3_f32 v224, v224, v9, v10
	v_min3_f32 v224, v224, v11, v4
	v_min3_f32 v224, v224, v5, v6
	v_min3_f32 v224, v224, v7, v0
	v_min3_f32 v224, v224, v1, v2
	v_min_f32_e32 v224, v224, v3
	s_waitcnt lgkmcnt(0)
	v_max_f32_e32 v71, v71, v71
	v_max_f32_e32 v72, v70, v71
	v_fma_f32 v225, v224, s85, -v72
	v_mul_f32_e32 v225, 0x3fb8aa3b, v225
	v_cmp_gt_f32_e32 vcc, s86, v225
	s_cbranch_vccnz .Lma_slow_gla
; DI void mem_attn_item(ldsp lds, const bf16_t* proj, int ldp, int qmcol, int gatecol, const bf16_t* kv, bf16_t* branch, int b0, int item, int tid, int wid, int lane, const bool stage = true) {
;     ...
;     float den = 0.f;
; #pragma unroll
;     for (int t = 0; t < 16; ++t)
; #pragma unroll
;         for (int j = 0; j < 4; ++j) { const float pv = exp2f((sacc[t][j] - mx) * 1.4426950408889634f); sacc[t][j] = pv; den += pv; }
;     den += __shfl_xor(den, 16); den += __shfl_xor(den, 32);
;     f32x4 oacc[4];
; #pragma unroll
;     for (int dt = 0; dt < 4; ++dt) oacc[dt] = (f32x4){0.f, 0.f, 0.f, 0.f};
; #pragma unroll
;     for (int kt = 0; kt < 8; ++kt) {
	v_fma_f32 v66, v66, s85, -v72
	v_mul_f32_e32 v70, 0x3fb8aa3b, v66
	v_fma_f32 v67, v67, s85, -v72
	v_fma_f32 v68, v68, s85, -v72
	v_exp_f32_e32 v66, v70
	v_mul_f32_e32 v71, 0x3fb8aa3b, v68
	v_fma_f32 v69, v69, s85, -v72
	v_mul_f32_e32 v70, 0x3fb8aa3b, v67
	v_fma_f32 v62, v62, s85, -v72
	v_fma_f32 v63, v63, s85, -v72
	v_exp_f32_e32 v67, v70
	v_fma_f32 v58, v58, s85, -v72
	v_exp_f32_e32 v68, v71
	v_add_f32_e32 v70, v66, v67
	v_fma_f32 v59, v59, s85, -v72
	v_mul_f32_e32 v71, 0x3fb8aa3b, v69
	v_add_f32_e32 v70, v68, v70
	v_fma_f32 v60, v60, s85, -v72
	v_exp_f32_e32 v69, v71
	v_fma_f32 v61, v61, s85, -v72
	v_fma_f32 v54, v54, s85, -v72
	v_add_f32_e32 v71, v69, v70
	v_mul_f32_e32 v70, 0x3fb8aa3b, v62
	v_fma_f32 v55, v55, s85, -v72
	v_fma_f32 v56, v56, s85, -v72
	v_exp_f32_e32 v62, v70
	v_fma_f32 v57, v57, s85, -v72
	v_fma_f32 v50, v50, s85, -v72
	v_mov_b32_e32 v70, v62
	v_add_f32_e32 v62, v70, v71
	v_mul_f32_e32 v71, 0x3fb8aa3b, v63
	v_fma_f32 v51, v51, s85, -v72
	v_fma_f32 v52, v52, s85, -v72
	v_exp_f32_e32 v63, v71
	v_fma_f32 v53, v53, s85, -v72
	v_fma_f32 v46, v46, s85, -v72
	v_mov_b32_e32 v71, v63
	v_fma_f32 v63, v64, s85, -v72
	v_mul_f32_e32 v64, 0x3fb8aa3b, v63
	v_fma_f32 v47, v47, s85, -v72
	v_fma_f32 v48, v48, s85, -v72
	v_exp_f32_e32 v63, v64
	v_fma_f32 v49, v49, s85, -v72
	v_fma_f32 v42, v42, s85, -v72
	v_mov_b32_e32 v64, v63
	v_fma_f32 v63, v65, s85, -v72
	v_mul_f32_e32 v65, 0x3fb8aa3b, v63
	v_fma_f32 v43, v43, s85, -v72
	v_fma_f32 v44, v44, s85, -v72
	v_exp_f32_e32 v63, v65
	v_fma_f32 v45, v45, s85, -v72
	v_fma_f32 v38, v38, s85, -v72
	v_mov_b32_e32 v65, v63
	v_mul_f32_e32 v63, 0x3fb8aa3b, v58
	v_fma_f32 v39, v39, s85, -v72
	v_fma_f32 v40, v40, s85, -v72
	v_exp_f32_e32 v58, v63
	v_fma_f32 v41, v41, s85, -v72
	v_fma_f32 v34, v34, s85, -v72
	v_mul_f32_e32 v63, 0x3fb8aa3b, v59
	v_fma_f32 v35, v35, s85, -v72
	v_fma_f32 v36, v36, s85, -v72
	v_exp_f32_e32 v59, v63
	v_add_f32_e32 v62, v71, v62
	v_add_f32_e32 v62, v64, v62
	v_mul_f32_e32 v63, 0x3fb8aa3b, v60
	v_add_f32_e32 v62, v65, v62
	v_add_f32_e32 v62, v58, v62
	v_exp_f32_e32 v60, v63
	v_add_f32_e32 v62, v59, v62
	v_fma_f32 v37, v37, s85, -v72
	v_mul_f32_e32 v63, 0x3fb8aa3b, v61
	v_add_f32_e32 v62, v60, v62
	v_fma_f32 v26, v26, s85, -v72
	v_exp_f32_e32 v61, v63
	v_fma_f32 v27, v27, s85, -v72
	v_fma_f32 v28, v28, s85, -v72
	v_mul_f32_e32 v63, 0x3fb8aa3b, v54
	v_add_f32_e32 v62, v61, v62
	v_fma_f32 v29, v29, s85, -v72
	v_exp_f32_e32 v54, v63
	v_fma_f32 v22, v22, s85, -v72
	v_fma_f32 v23, v23, s85, -v72
	v_mul_f32_e32 v63, 0x3fb8aa3b, v55
	v_add_f32_e32 v62, v54, v62
	v_fma_f32 v24, v24, s85, -v72
	v_exp_f32_e32 v55, v63
	v_fma_f32 v25, v25, s85, -v72
	v_fma_f32 v18, v18, s85, -v72
	v_mul_f32_e32 v63, 0x3fb8aa3b, v56
	v_add_f32_e32 v62, v55, v62
	v_fma_f32 v19, v19, s85, -v72
	v_exp_f32_e32 v56, v63
	v_fma_f32 v14, v14, s85, -v72
	v_fma_f32 v15, v15, s85, -v72
	v_mul_f32_e32 v63, 0x3fb8aa3b, v57
	v_add_f32_e32 v62, v56, v62
	v_fma_f32 v16, v16, s85, -v72
	v_exp_f32_e32 v57, v63
	v_fma_f32 v17, v17, s85, -v72
	v_fma_f32 v8, v8, s85, -v72
	v_mul_f32_e32 v63, 0x3fb8aa3b, v50
	v_add_f32_e32 v62, v57, v62
	v_fma_f32 v9, v9, s85, -v72
	v_exp_f32_e32 v50, v63
	v_fma_f32 v10, v10, s85, -v72
	v_fma_f32 v11, v11, s85, -v72
	v_mul_f32_e32 v63, 0x3fb8aa3b, v51
	v_add_f32_e32 v62, v50, v62
	v_fma_f32 v4, v4, s85, -v72
	v_exp_f32_e32 v51, v63
	v_fma_f32 v5, v5, s85, -v72
	v_fma_f32 v6, v6, s85, -v72
	v_mul_f32_e32 v63, 0x3fb8aa3b, v52
	v_add_f32_e32 v62, v51, v62
	v_fma_f32 v7, v7, s85, -v72
	v_exp_f32_e32 v52, v63
	v_fma_f32 v0, v0, s85, -v72
	v_fma_f32 v1, v1, s85, -v72
	v_mul_f32_e32 v63, 0x3fb8aa3b, v53
	v_add_f32_e32 v62, v52, v62
	v_fma_f32 v2, v2, s85, -v72
	v_exp_f32_e32 v53, v63
	v_fma_f32 v3, v3, s85, -v72
	v_cvt_pk_bf16_f32 v66, v66, v67
	v_mul_f32_e32 v63, 0x3fb8aa3b, v46
	v_add_f32_e32 v62, v53, v62
	v_cvt_pk_bf16_f32 v67, v68, v69
	v_exp_f32_e32 v46, v63
	v_cvt_pk_bf16_f32 v68, v70, v71
	v_cvt_pk_bf16_f32 v69, v64, v65
	v_mul_f32_e32 v63, 0x3fb8aa3b, v47
	v_add_f32_e32 v62, v46, v62
	v_cvt_pk_bf16_f32 v58, v58, v59
	v_exp_f32_e32 v47, v63
	v_cvt_pk_bf16_f32 v59, v60, v61
	v_cvt_pk_bf16_f32 v60, v54, v55
	v_mul_f32_e32 v63, 0x3fb8aa3b, v48
	v_add_f32_e32 v62, v47, v62
	v_cvt_pk_bf16_f32 v61, v56, v57
	v_exp_f32_e32 v48, v63
	v_cvt_pk_bf16_f32 v50, v50, v51
	v_cvt_pk_bf16_f32 v51, v52, v53
	v_mul_f32_e32 v63, 0x3fb8aa3b, v49
	v_add_f32_e32 v62, v48, v62
	v_cvt_pk_bf16_f32 v52, v46, v47
	v_exp_f32_e32 v49, v63
	v_mul_f32_e32 v63, 0x3fb8aa3b, v42
	v_add_f32_e32 v62, v49, v62
	v_cvt_pk_bf16_f32 v53, v48, v49
	v_exp_f32_e32 v42, v63
	v_mul_f32_e32 v63, 0x3fb8aa3b, v43
	v_add_f32_e32 v62, v42, v62
	s_nop 0
	v_exp_f32_e32 v43, v63
	v_mul_f32_e32 v63, 0x3fb8aa3b, v44
	v_add_f32_e32 v62, v43, v62
	v_cvt_pk_bf16_f32 v42, v42, v43
	v_exp_f32_e32 v44, v63
	v_mul_f32_e32 v63, 0x3fb8aa3b, v45
	v_add_f32_e32 v62, v44, v62
	s_nop 0
	v_exp_f32_e32 v45, v63
	v_mul_f32_e32 v63, 0x3fb8aa3b, v38
	v_add_f32_e32 v62, v45, v62
	v_cvt_pk_bf16_f32 v43, v44, v45
	v_exp_f32_e32 v38, v63
	v_mul_f32_e32 v63, 0x3fb8aa3b, v39
	v_add_f32_e32 v62, v38, v62
	s_nop 0
	v_exp_f32_e32 v39, v63
	v_mul_f32_e32 v63, 0x3fb8aa3b, v40
	v_add_f32_e32 v62, v39, v62
	v_cvt_pk_bf16_f32 v44, v38, v39
	v_exp_f32_e32 v40, v63
	v_mul_f32_e32 v63, 0x3fb8aa3b, v41
	v_add_f32_e32 v62, v40, v62
	s_nop 0
	v_exp_f32_e32 v41, v63
	v_mul_f32_e32 v63, 0x3fb8aa3b, v34
	v_add_f32_e32 v62, v41, v62
	v_cvt_pk_bf16_f32 v45, v40, v41
	v_exp_f32_e32 v34, v63
	v_mul_f32_e32 v63, 0x3fb8aa3b, v35
	v_add_f32_e32 v62, v34, v62
	s_nop 0
	v_exp_f32_e32 v35, v63
	v_mul_f32_e32 v63, 0x3fb8aa3b, v36
	v_add_f32_e32 v62, v35, v62
	v_cvt_pk_bf16_f32 v34, v34, v35
; DI unsigned cvt_pk_bf16(float lo, float hi) { const f32x2_t v = {lo, hi}; const bf16v2_t b = __builtin_convertvector(v, bf16v2_t); return __builtin_bit_cast(unsigned, b); }
; DI f32x4 mfma16(bf16x8 a, bf16x8 b, f32x4 c) { return __builtin_amdgcn_mfma_f32_16x16x32_bf16(a, b, c, 0, 0, 0); }
; DI void mem_attn_item(ldsp lds, const bf16_t* proj, int ldp, int qmcol, int gatecol, const bf16_t* kv, bf16_t* branch, int b0, int item, int tid, int wid, int lane, const bool stage = true) {
;     ...
;     for (int t = 0; t < 16; ++t)
; #pragma unroll
;         for (int j = 0; j < 4; ++j) { const float pv = exp2f((sacc[t][j] - mx) * 1.4426950408889634f); sacc[t][j] = pv; den += pv; }
;     den += __shfl_xor(den, 16); den += __shfl_xor(den, 32);
;     f32x4 oacc[4];
; #pragma unroll
;     for (int dt = 0; dt < 4; ++dt) oacc[dt] = (f32x4){0.f, 0.f, 0.f, 0.f};
; #pragma unroll
;     for (int kt = 0; kt < 8; ++kt) {
;         u32x4 pw; pw.x = cvt_pk_bf16(sacc[2 * kt][0], sacc[2 * kt][1]); pw.y = cvt_pk_bf16(sacc[2 * kt][2], sacc[2 * kt][3]);
;         pw.z = cvt_pk_bf16(sacc[2 * kt + 1][0], sacc[2 * kt + 1][1]); pw.w = cvt_pk_bf16(sacc[2 * kt + 1][2], sacc[2 * kt + 1][3]);
;         const bf16x8 pf = __builtin_bit_cast(bf16x8, pw);
;         const ldsp va = Vb + (32 * kt + quad * 4 + (li >> 2)) * KS + (li & 3) * 8;
; #pragma unroll
;         for (int dt = 0; dt < 4; ++dt) oacc[dt] = mfma16(lds_tr8(va + dt * 32, va + 16 * KS + dt * 32), pf, oacc[dt]);
;     }
	v_exp_f32_e32 v36, v63
	v_mul_f32_e32 v63, 0x3fb8aa3b, v37
	v_add_f32_e32 v62, v36, v62
	s_nop 0
	v_exp_f32_e32 v37, v63
	v_mul_f32_e32 v63, 0x3fb8aa3b, v26
	v_add_f32_e32 v62, v37, v62
	v_cvt_pk_bf16_f32 v35, v36, v37
	v_exp_f32_e32 v26, v63
	v_mul_f32_e32 v63, 0x3fb8aa3b, v27
	v_add_f32_e32 v62, v26, v62
	s_nop 0
	v_exp_f32_e32 v27, v63
	s_nop 0
	v_add_f32_e32 v63, v27, v62
	v_mul_f32_e32 v62, 0x3fb8aa3b, v28
	v_cvt_pk_bf16_f32 v36, v26, v27
	s_nop 0
	v_exp_f32_e32 v28, v62
	s_nop 0
	v_mov_b32_e32 v62, v28
	v_add_f32_e32 v28, v62, v63
	v_mul_f32_e32 v63, 0x3fb8aa3b, v29
	s_nop 1
	v_exp_f32_e32 v29, v63
	s_nop 0
	v_mov_b32_e32 v63, v29
	v_mul_f32_e32 v29, 0x3fb8aa3b, v22
	v_add_f32_e32 v28, v63, v28
	v_cvt_pk_bf16_f32 v37, v62, v63
	v_exp_f32_e32 v22, v29
	v_mul_f32_e32 v29, 0x3fb8aa3b, v23
	v_add_f32_e32 v28, v22, v28
	s_nop 0
	v_exp_f32_e32 v23, v29
	v_mul_f32_e32 v29, 0x3fb8aa3b, v24
	v_add_f32_e32 v28, v23, v28
	v_cvt_pk_bf16_f32 v22, v22, v23
	v_exp_f32_e32 v24, v29
	v_mul_f32_e32 v29, 0x3fb8aa3b, v25
	v_add_f32_e32 v28, v24, v28
	s_nop 0
	v_exp_f32_e32 v25, v29
	s_nop 0
	v_add_f32_e32 v29, v25, v28
	v_mul_f32_e32 v28, 0x3fb8aa3b, v18
	v_cvt_pk_bf16_f32 v23, v24, v25
	s_nop 0
	v_exp_f32_e32 v18, v28
	s_nop 0
	v_mov_b32_e32 v28, v18
	v_add_f32_e32 v18, v28, v29
	v_mul_f32_e32 v29, 0x3fb8aa3b, v19
	s_nop 1
	v_exp_f32_e32 v19, v29
	s_nop 0
	v_mov_b32_e32 v29, v19
	v_fma_f32 v19, v20, s85, -v72
	v_mul_f32_e32 v20, 0x3fb8aa3b, v19
	v_add_f32_e32 v18, v29, v18
	v_cvt_pk_bf16_f32 v24, v28, v29
	v_exp_f32_e32 v19, v20
	s_nop 0
	v_mov_b32_e32 v20, v19
	v_fma_f32 v19, v21, s85, -v72
	v_mul_f32_e32 v21, 0x3fb8aa3b, v19
	ds_read_b64_tr_b16 v[72:73], v97 offset:39168
	ds_read_b64_tr_b16 v[70:71], v97 offset:36864
	ds_read_b64_tr_b16 v[108:109], v97 offset:36896
	v_exp_f32_e32 v19, v21
	ds_read_b64_tr_b16 v[110:111], v97 offset:39200
	ds_read_b64_tr_b16 v[112:113], v97 offset:36928
	ds_read_b64_tr_b16 v[114:115], v97 offset:39232
	v_mov_b32_e32 v21, v19
	v_mul_f32_e32 v19, 0x3fb8aa3b, v14
	ds_read_b64_tr_b16 v[116:117], v97 offset:36960
	ds_read_b64_tr_b16 v[118:119], v97 offset:39264
	v_exp_f32_e32 v14, v19
	ds_read_b64_tr_b16 v[54:55], v97 offset:41472
	ds_read_b64_tr_b16 v[56:57], v97 offset:43776
	s_waitcnt lgkmcnt(8)
	v_mfma_f32_16x16x32_bf16 v[70:73], v[70:73], v[66:69], 0
	v_mul_f32_e32 v19, 0x3fb8aa3b, v15
	s_waitcnt lgkmcnt(6)
	v_mfma_f32_16x16x32_bf16 v[108:111], v[108:111], v[66:69], 0
	v_cvt_pk_bf16_f32 v25, v20, v21
	v_exp_f32_e32 v15, v19
	s_waitcnt lgkmcnt(4)
	v_mfma_f32_16x16x32_bf16 v[112:115], v[112:115], v[66:69], 0
	v_add_f32_e32 v18, v20, v18
	v_mul_f32_e32 v19, 0x3fb8aa3b, v16
	s_waitcnt lgkmcnt(2)
	v_mfma_f32_16x16x32_bf16 v[64:67], v[116:119], v[66:69], 0
	v_add_f32_e32 v18, v21, v18
	v_exp_f32_e32 v16, v19
	s_waitcnt lgkmcnt(0)
	v_mfma_f32_16x16x32_bf16 v[54:57], v[54:57], v[58:61], v[70:73]
	ds_read_b64_tr_b16 v[68:69], v97 offset:41504
	s_nop 1
	ds_read_b64_tr_b16 v[70:71], v97 offset:43808
	v_mul_f32_e32 v19, 0x3fb8aa3b, v17
	s_waitcnt lgkmcnt(0)
	v_mfma_f32_16x16x32_bf16 v[68:71], v[68:71], v[58:61], v[108:111]
	v_exp_f32_e32 v17, v19
	s_nop 1
	ds_read_b64_tr_b16 v[108:109], v97 offset:41536
	ds_read_b64_tr_b16 v[110:111], v97 offset:43840
	s_waitcnt lgkmcnt(0)
	v_mfma_f32_16x16x32_bf16 v[108:111], v[108:111], v[58:61], v[112:115]
	v_mul_f32_e32 v19, 0x3fb8aa3b, v8
	s_nop 1
	ds_read_b64_tr_b16 v[112:113], v97 offset:41568
	ds_read_b64_tr_b16 v[114:115], v97 offset:43872
	v_exp_f32_e32 v8, v19
	ds_read_b64_tr_b16 v[46:47], v97 offset:46080
	ds_read_b64_tr_b16 v[48:49], v97 offset:48384
	s_waitcnt lgkmcnt(0)
	v_mfma_f32_16x16x32_bf16 v[46:49], v[46:49], v[50:53], v[54:57]
	v_mul_f32_e32 v19, 0x3fb8aa3b, v9
	s_nop 1
	ds_read_b64_tr_b16 v[54:55], v97 offset:46112
	ds_read_b64_tr_b16 v[56:57], v97 offset:48416
	v_exp_f32_e32 v9, v19
	v_mfma_f32_16x16x32_bf16 v[58:61], v[112:115], v[58:61], v[64:67]
	s_nop 2
	ds_read_b64_tr_b16 v[64:65], v97 offset:46144
	ds_read_b64_tr_b16 v[66:67], v97 offset:48448
	v_mul_f32_e32 v19, 0x3fb8aa3b, v10
	s_waitcnt lgkmcnt(2)
; DI unsigned cvt_pk_bf16(float lo, float hi) { const f32x2_t v = {lo, hi}; const bf16v2_t b = __builtin_convertvector(v, bf16v2_t); return __builtin_bit_cast(unsigned, b); }
; DI f32x4 mfma16(bf16x8 a, bf16x8 b, f32x4 c) { return __builtin_amdgcn_mfma_f32_16x16x32_bf16(a, b, c, 0, 0, 0); }
; DI void mem_attn_item(ldsp lds, const bf16_t* proj, int ldp, int qmcol, int gatecol, const bf16_t* kv, bf16_t* branch, int b0, int item, int tid, int wid, int lane, const bool stage = true) {
;     ...
; #pragma unroll
;     for (int kt = 0; kt < 8; ++kt) {
;         u32x4 pw; pw.x = cvt_pk_bf16(sacc[2 * kt][0], sacc[2 * kt][1]); pw.y = cvt_pk_bf16(sacc[2 * kt][2], sacc[2 * kt][3]);
;         pw.z = cvt_pk_bf16(sacc[2 * kt + 1][0], sacc[2 * kt + 1][1]); pw.w = cvt_pk_bf16(sacc[2 * kt + 1][2], sacc[2 * kt + 1][3]);
;         const bf16x8 pf = __builtin_bit_cast(bf16x8, pw);
;         const ldsp va = Vb + (32 * kt + quad * 4 + (li >> 2)) * KS + (li & 3) * 8;
; #pragma unroll
;         for (int dt = 0; dt < 4; ++dt) oacc[dt] = mfma16(lds_tr8(va + dt * 32, va + 16 * KS + dt * 32), pf, oacc[dt]);
;     }
	v_mfma_f32_16x16x32_bf16 v[54:57], v[54:57], v[50:53], v[68:71]
	s_nop 2
	ds_read_b64_tr_b16 v[68:69], v97 offset:46176
	ds_read_b64_tr_b16 v[70:71], v97 offset:48480
	v_exp_f32_e32 v10, v19
	ds_read_b64_tr_b16 v[38:39], v97 offset:50688
	ds_read_b64_tr_b16 v[40:41], v97 offset:52992
	s_waitcnt lgkmcnt(0)
	v_mfma_f32_16x16x32_bf16 v[38:41], v[38:41], v[42:45], v[46:49]
	v_mul_f32_e32 v19, 0x3fb8aa3b, v11
	s_nop 1
	ds_read_b64_tr_b16 v[46:47], v97 offset:50720
	ds_read_b64_tr_b16 v[48:49], v97 offset:53024
	v_exp_f32_e32 v11, v19
	v_mfma_f32_16x16x32_bf16 v[64:67], v[64:67], v[50:53], v[108:111]
	v_add_f32_e32 v18, v14, v18
	v_mul_f32_e32 v19, 0x3fb8aa3b, v4
	v_mfma_f32_16x16x32_bf16 v[50:53], v[68:71], v[50:53], v[58:61]
	v_add_f32_e32 v18, v15, v18
	v_exp_f32_e32 v4, v19
	s_waitcnt lgkmcnt(0)
	v_mfma_f32_16x16x32_bf16 v[46:49], v[46:49], v[42:45], v[54:57]
	s_nop 2
	ds_read_b64_tr_b16 v[54:55], v97 offset:50752
	ds_read_b64_tr_b16 v[56:57], v97 offset:53056
	v_mul_f32_e32 v19, 0x3fb8aa3b, v5
	ds_read_b64_tr_b16 v[58:59], v97 offset:50784
	ds_read_b64_tr_b16 v[60:61], v97 offset:53088
	v_exp_f32_e32 v5, v19
	s_waitcnt lgkmcnt(2)
	v_mfma_f32_16x16x32_bf16 v[54:57], v[54:57], v[42:45], v[64:67]
	v_add_f32_e32 v18, v16, v18
	v_mul_f32_e32 v19, 0x3fb8aa3b, v6
	s_waitcnt lgkmcnt(0)
	v_mfma_f32_16x16x32_bf16 v[42:45], v[58:61], v[42:45], v[50:53]
	s_nop 2
	ds_read_b64_tr_b16 v[50:51], v97 offset:55296
	ds_read_b64_tr_b16 v[52:53], v97 offset:57600
	v_exp_f32_e32 v6, v19
	s_waitcnt lgkmcnt(0)
	v_mfma_f32_16x16x32_bf16 v[38:41], v[50:53], v[34:37], v[38:41]
	ds_read_b64_tr_b16 v[50:51], v97 offset:55328
	ds_read_b64_tr_b16 v[52:53], v97 offset:57632
	v_mul_f32_e32 v19, 0x3fb8aa3b, v7
	s_waitcnt lgkmcnt(0)
	v_mfma_f32_16x16x32_bf16 v[46:49], v[50:53], v[34:37], v[46:49]
	v_exp_f32_e32 v7, v19
	ds_read_b64_tr_b16 v[50:51], v97 offset:55360
	ds_read_b64_tr_b16 v[52:53], v97 offset:57664
	s_waitcnt lgkmcnt(0)
	v_mfma_f32_16x16x32_bf16 v[50:53], v[50:53], v[34:37], v[54:57]
	v_mul_f32_e32 v19, 0x3fb8aa3b, v0
	s_nop 1
	ds_read_b64_tr_b16 v[54:55], v97 offset:55392
	ds_read_b64_tr_b16 v[56:57], v97 offset:57696
	v_exp_f32_e32 v0, v19
	ds_read_b64_tr_b16 v[26:27], v97 offset:59904
	ds_read_b64_tr_b16 v[28:29], v97 offset:62208
	s_waitcnt lgkmcnt(0)
	v_mfma_f32_16x16x32_bf16 v[26:29], v[26:29], v[22:25], v[38:41]
	v_mul_f32_e32 v19, 0x3fb8aa3b, v1
	s_nop 1
	ds_read_b64_tr_b16 v[38:39], v97 offset:59936
	ds_read_b64_tr_b16 v[40:41], v97 offset:62240
	v_exp_f32_e32 v1, v19
	v_mfma_f32_16x16x32_bf16 v[34:37], v[54:57], v[34:37], v[42:45]
	s_nop 2
	ds_read_b64_tr_b16 v[42:43], v97 offset:59968
	ds_read_b64_tr_b16 v[44:45], v97 offset:62272
	v_add_f32_e32 v18, v17, v18
	s_waitcnt lgkmcnt(2)
	v_mfma_f32_16x16x32_bf16 v[38:41], v[38:41], v[22:25], v[46:49]
	s_nop 2
	ds_read_b64_tr_b16 v[46:47], v97 offset:60000
	ds_read_b64_tr_b16 v[48:49], v97 offset:62304
	v_add_f32_e32 v18, v8, v18
	v_mul_f32_e32 v19, 0x3fb8aa3b, v2
	v_add_f32_e32 v18, v9, v18
	v_add_f32_e32 v18, v10, v18
	v_add_f32_e32 v18, v11, v18
	s_waitcnt lgkmcnt(2)
	v_mfma_f32_16x16x32_bf16 v[42:45], v[42:45], v[22:25], v[50:53]
	v_cvt_pk_bf16_f32 v14, v14, v15
	v_cvt_pk_bf16_f32 v15, v16, v17
	v_cvt_pk_bf16_f32 v16, v8, v9
	s_waitcnt lgkmcnt(0)
	v_mfma_f32_16x16x32_bf16 v[20:23], v[46:49], v[22:25], v[34:37]
	v_cvt_pk_bf16_f32 v17, v10, v11
	ds_read_b64_tr_b16 v[8:9], v97 offset:64512
	ds_read_b64_tr_b16 v[10:11], v98 offset:29952
	ds_read_b64_tr_b16 v[36:37], v98 offset:29984
	ds_read_b64_tr_b16 v[34:35], v97 offset:64544
	v_exp_f32_e32 v2, v19
	v_add_f32_e32 v18, v4, v18
	v_add_f32_e32 v18, v5, v18
	v_mul_f32_e32 v19, 0x3fb8aa3b, v3
	v_add_f32_e32 v18, v6, v18
	s_waitcnt lgkmcnt(2)
	v_mfma_f32_16x16x32_bf16 v[8:11], v[8:11], v[14:17], v[26:29]
	v_exp_f32_e32 v3, v19
	s_waitcnt lgkmcnt(0)
	v_mfma_f32_16x16x32_bf16 v[24:27], v[34:37], v[14:17], v[38:41]
	ds_read_b64_tr_b16 v[34:35], v97 offset:64576
	ds_read_b64_tr_b16 v[36:37], v98 offset:30016
	s_nop 0
	ds_read_b64_tr_b16 v[38:39], v97 offset:64608
	ds_read_b64_tr_b16 v[40:41], v98 offset:30048
	v_add_f32_e32 v18, v7, v18
	v_add_f32_e32 v18, v0, v18
	v_add_f32_e32 v18, v1, v18
	v_add_f32_e32 v18, v2, v18
	s_branch .Lma_join_gla
